# v32: v31 + int8 GEMM1 K-loop LDS-DMA balance 3/5 (SP1 segments, which carry 16 fragment reads, stage 3; SP2 segments stage 5)
# baseline (speedup 1.0000x reference)
.LBB0_300:
	s_add_u32 s100, s0, 0xfff80000
	s_addc_u32 s101, s1, -1
	s_add_u32 s28, s0, 0xfff80080
	s_addc_u32 s29, s1, -1
	s_add_i32 s42, 0, 0x10000
	s_cmp_eq_u32 s41, 28
	s_cselect_b32 s31, s18, s29
	s_cselect_b32 s30, s19, s28
	v_add_u32_e32 v0, s42, v199
	s_cselect_b32 s29, s27, s40
	s_cselect_b32 s28, s34, s35
	s_add_i32 s49, 0, 0x14000
	ds_read_b128 v[2:5], v0
	ds_read_b128 v[6:9], v0 offset:1024
	ds_read_b128 v[10:13], v0 offset:2048
	ds_read_b128 v[14:17], v0 offset:3072
	v_add_u32_e32 v0, s49, v199
	ds_read_b128 v[146:149], v0
	ds_read_b128 v[150:153], v0 offset:1024
	ds_read_b128 v[154:157], v0 offset:2048
	ds_read_b128 v[158:161], v0 offset:3072
	s_mov_b32 m0, s88
	ds_read_b128 v[174:177], v250
	ds_read_b128 v[178:181], v250 offset:1024
	ds_read_b128 v[182:185], v250 offset:2048
	ds_read_b128 v[186:189], v250 offset:3072
	ds_read_b128 v[190:193], v250 offset:4096
	ds_read_b128 v[200:203], v250 offset:5120
	ds_read_b128 v[204:207], v250 offset:6144
	ds_read_b128 v[208:211], v250 offset:7168
	global_load_lds_dwordx4 v166, s[100:101]
	s_add_i32 m0, s21, 0xc000
	s_nop 0
	global_load_lds_dwordx4 v170, s[0:1]
	s_add_i32 m0, s21, 0xe000
	s_nop 0
	global_load_lds_dwordx4 v172, s[0:1]
	s_cmp_eq_u32 s41, 28
	s_cbranch_scc1 .Lspf_w0
	s_waitcnt vmcnt(8)
	s_branch .Lspf_j0

.Lspf_j0:
	s_waitcnt lgkmcnt(0)
	s_barrier
	s_waitcnt lgkmcnt(0)
	v_mfma_i32_16x16x64_i8 v[142:145], v[2:5], v[174:177], v[142:145]
	v_mfma_i32_16x16x64_i8 v[142:145], v[6:9], v[178:181], v[142:145]
	v_mfma_i32_16x16x64_i8 v[134:137], v[2:5], v[182:185], v[134:137]
	v_mfma_i32_16x16x64_i8 v[134:137], v[6:9], v[186:189], v[134:137]
	v_mfma_i32_16x16x64_i8 v[122:125], v[2:5], v[190:193], v[122:125]
	v_mfma_i32_16x16x64_i8 v[122:125], v[6:9], v[200:203], v[122:125]
	v_mfma_i32_16x16x64_i8 v[106:109], v[2:5], v[204:207], v[106:109]
	v_mfma_i32_16x16x64_i8 v[106:109], v[6:9], v[208:211], v[106:109]
	v_mfma_i32_16x16x64_i8 v[138:141], v[10:13], v[174:177], v[138:141]
	v_mfma_i32_16x16x64_i8 v[138:141], v[14:17], v[178:181], v[138:141]
	v_mfma_i32_16x16x64_i8 v[130:133], v[10:13], v[182:185], v[130:133]
	v_mfma_i32_16x16x64_i8 v[130:133], v[14:17], v[186:189], v[130:133]
	v_mfma_i32_16x16x64_i8 v[114:117], v[10:13], v[190:193], v[114:117]
	v_mfma_i32_16x16x64_i8 v[114:117], v[14:17], v[200:203], v[114:117]
	v_mfma_i32_16x16x64_i8 v[98:101], v[10:13], v[204:207], v[98:101]
	v_mfma_i32_16x16x64_i8 v[98:101], v[14:17], v[208:211], v[98:101]
	v_mfma_i32_16x16x64_i8 v[126:129], v[146:149], v[174:177], v[126:129]
	v_mfma_i32_16x16x64_i8 v[126:129], v[150:153], v[178:181], v[126:129]
	v_mfma_i32_16x16x64_i8 v[110:113], v[146:149], v[182:185], v[110:113]
	v_mfma_i32_16x16x64_i8 v[110:113], v[150:153], v[186:189], v[110:113]
	v_mfma_i32_16x16x64_i8 v[94:97], v[146:149], v[190:193], v[94:97]
	v_mfma_i32_16x16x64_i8 v[94:97], v[150:153], v[200:203], v[94:97]
	v_mfma_i32_16x16x64_i8 v[86:89], v[146:149], v[204:207], v[86:89]
	v_mfma_i32_16x16x64_i8 v[86:89], v[150:153], v[208:211], v[86:89]
	v_mfma_i32_16x16x64_i8 v[118:121], v[154:157], v[174:177], v[118:121]
	v_mfma_i32_16x16x64_i8 v[118:121], v[158:161], v[178:181], v[118:121]
	v_mfma_i32_16x16x64_i8 v[102:105], v[154:157], v[182:185], v[102:105]
	v_mfma_i32_16x16x64_i8 v[102:105], v[158:161], v[186:189], v[102:105]
	v_mfma_i32_16x16x64_i8 v[90:93], v[154:157], v[190:193], v[90:93]
	v_mfma_i32_16x16x64_i8 v[90:93], v[158:161], v[200:203], v[90:93]
	v_mfma_i32_16x16x64_i8 v[82:85], v[154:157], v[204:207], v[82:85]
	v_mfma_i32_16x16x64_i8 v[82:85], v[158:161], v[208:211], v[82:85]
	s_barrier
	s_add_i32 s42, s42, s81
	s_mov_b32 m0, s42
	ds_read_b128 v[174:177], v250 offset:16384
	ds_read_b128 v[178:181], v250 offset:17408
	ds_read_b128 v[182:185], v250 offset:18432
	ds_read_b128 v[186:189], v250 offset:19456
	ds_read_b128 v[190:193], v250 offset:20480
	ds_read_b128 v[200:203], v250 offset:21504
	ds_read_b128 v[204:207], v250 offset:22528
	ds_read_b128 v[208:211], v250 offset:23552
	global_load_lds_dwordx4 v164, s[28:29]
	s_add_i32 m0, s42, 0x2000
	s_add_u32 s42, s28, 0x80000
	s_addc_u32 s43, s29, 0
	s_add_i32 s49, s49, s81
	global_load_lds_dwordx4 v168, s[28:29]
	s_mov_b32 m0, s49
	s_nop 0
	global_load_lds_dwordx4 v164, s[42:43]
	s_add_i32 m0, s49, 0x2000
	s_nop 0
	global_load_lds_dwordx4 v168, s[42:43]
	s_mov_b32 m0, s21
	s_nop 0
	global_load_lds_dwordx4 v162, s[30:31]
	s_cmp_eq_u32 s41, 28
	s_cbranch_scc1 .Lspf_w1
	s_waitcnt vmcnt(7)
	s_branch .Lspf_j1
.Lspf_w1:
	s_waitcnt vmcnt(19)
.Lspf_j1:
	s_waitcnt lgkmcnt(0)
	s_barrier
	s_waitcnt lgkmcnt(0)
	v_mfma_i32_16x16x64_i8 v[78:81], v[2:5], v[174:177], v[78:81]
	v_mfma_i32_16x16x64_i8 v[78:81], v[6:9], v[178:181], v[78:81]
	v_mfma_i32_16x16x64_i8 v[74:77], v[10:13], v[174:177], v[74:77]
	v_mfma_i32_16x16x64_i8 v[74:77], v[14:17], v[178:181], v[74:77]
	v_mfma_i32_16x16x64_i8 v[70:73], v[2:5], v[182:185], v[70:73]
	v_mfma_i32_16x16x64_i8 v[70:73], v[6:9], v[186:189], v[70:73]
	v_mfma_i32_16x16x64_i8 v[66:69], v[10:13], v[182:185], v[66:69]
	v_mfma_i32_16x16x64_i8 v[66:69], v[14:17], v[186:189], v[66:69]
	v_mfma_i32_16x16x64_i8 v[54:57], v[2:5], v[190:193], v[54:57]
	v_mfma_i32_16x16x64_i8 v[54:57], v[6:9], v[200:203], v[54:57]
	v_mfma_i32_16x16x64_i8 v[50:53], v[10:13], v[190:193], v[50:53]
	v_mfma_i32_16x16x64_i8 v[50:53], v[14:17], v[200:203], v[50:53]
	v_mfma_i32_16x16x64_i8 v[2:5], v[2:5], v[204:207], v[38:41]
	v_mfma_i32_16x16x64_i8 v[2:5], v[6:9], v[208:211], v[2:5]
	v_mfma_i32_16x16x64_i8 v[6:9], v[10:13], v[204:207], v[34:37]
	v_mfma_i32_16x16x64_i8 v[6:9], v[14:17], v[208:211], v[6:9]
	v_mfma_i32_16x16x64_i8 v[34:37], v[146:149], v[182:185], v[46:49]
	v_mfma_i32_16x16x64_i8 v[46:49], v[150:153], v[186:189], v[34:37]
	v_mfma_i32_16x16x64_i8 v[34:37], v[154:157], v[182:185], v[42:45]
	v_mfma_i32_16x16x64_i8 v[42:45], v[158:161], v[186:189], v[34:37]
	v_mfma_i32_16x16x64_i8 v[30:33], v[146:149], v[190:193], v[30:33]
	v_mfma_i32_16x16x64_i8 v[30:33], v[150:153], v[200:203], v[30:33]
	v_mfma_i32_16x16x64_i8 v[26:29], v[154:157], v[190:193], v[26:29]
	v_mfma_i32_16x16x64_i8 v[26:29], v[158:161], v[200:203], v[26:29]
	v_mfma_i32_16x16x64_i8 v[22:25], v[146:149], v[204:207], v[22:25]
	v_mfma_i32_16x16x64_i8 v[22:25], v[150:153], v[208:211], v[22:25]
	v_mfma_i32_16x16x64_i8 v[18:21], v[154:157], v[204:207], v[18:21]
	v_mfma_i32_16x16x64_i8 v[18:21], v[158:161], v[208:211], v[18:21]
	v_mfma_i32_16x16x64_i8 v[10:13], v[146:149], v[174:177], v[62:65]
	v_mfma_i32_16x16x64_i8 v[10:13], v[150:153], v[178:181], v[10:13]
	v_mfma_i32_16x16x64_i8 v[14:17], v[154:157], v[174:177], v[58:61]
	v_mfma_i32_16x16x64_i8 v[14:17], v[158:161], v[178:181], v[14:17]
	s_barrier
	s_add_i32 s42, 0, 0x18000
	v_add_u32_e32 v0, s42, v199
	s_add_i32 s43, 0, 0x1c000
	ds_read_b128 v[34:37], v0
	ds_read_b128 v[38:41], v0 offset:1024
	ds_read_b128 v[58:61], v0 offset:2048
	ds_read_b128 v[62:65], v0 offset:3072
	v_add_u32_e32 v0, s43, v199
	ds_read_b128 v[146:149], v0
	ds_read_b128 v[150:153], v0 offset:1024
	ds_read_b128 v[154:157], v0 offset:2048
	ds_read_b128 v[158:161], v0 offset:3072
	s_mov_b32 m0, s57
	ds_read_b128 v[174:177], v250 offset:32768
	ds_read_b128 v[178:181], v250 offset:33792
	ds_read_b128 v[182:185], v250 offset:34816
	ds_read_b128 v[186:189], v250 offset:35840
	ds_read_b128 v[190:193], v250 offset:36864
	ds_read_b128 v[200:203], v250 offset:37888
	ds_read_b128 v[204:207], v250 offset:38912
	ds_read_b128 v[208:211], v250 offset:39936
	global_load_lds_dwordx4 v166, s[30:31]
	s_add_u32 s30, s30, 0x80000
	s_addc_u32 s31, s31, 0
	s_mov_b32 m0, s73
	s_nop 0
	global_load_lds_dwordx4 v162, s[30:31]
	s_mov_b32 m0, s76
	s_nop 0
	global_load_lds_dwordx4 v166, s[30:31]
	s_cmp_eq_u32 s41, 28
	s_cbranch_scc1 .Lspf_w2
	s_waitcnt vmcnt(8)
	s_branch .Lspf_j2

.Lspf_j2:
	s_waitcnt lgkmcnt(0)
	s_barrier
	s_waitcnt lgkmcnt(0)
	v_mfma_i32_16x16x64_i8 v[142:145], v[34:37], v[174:177], v[142:145]
	v_mfma_i32_16x16x64_i8 v[142:145], v[38:41], v[178:181], v[142:145]
	v_mfma_i32_16x16x64_i8 v[134:137], v[34:37], v[182:185], v[134:137]
	v_mfma_i32_16x16x64_i8 v[134:137], v[38:41], v[186:189], v[134:137]
	v_mfma_i32_16x16x64_i8 v[122:125], v[34:37], v[190:193], v[122:125]
	v_mfma_i32_16x16x64_i8 v[122:125], v[38:41], v[200:203], v[122:125]
	v_mfma_i32_16x16x64_i8 v[106:109], v[34:37], v[204:207], v[106:109]
	v_mfma_i32_16x16x64_i8 v[106:109], v[38:41], v[208:211], v[106:109]
	v_mfma_i32_16x16x64_i8 v[138:141], v[58:61], v[174:177], v[138:141]
	v_mfma_i32_16x16x64_i8 v[138:141], v[62:65], v[178:181], v[138:141]
	v_mfma_i32_16x16x64_i8 v[130:133], v[58:61], v[182:185], v[130:133]
	v_mfma_i32_16x16x64_i8 v[130:133], v[62:65], v[186:189], v[130:133]
	v_mfma_i32_16x16x64_i8 v[114:117], v[58:61], v[190:193], v[114:117]
	v_mfma_i32_16x16x64_i8 v[114:117], v[62:65], v[200:203], v[114:117]
	v_mfma_i32_16x16x64_i8 v[98:101], v[58:61], v[204:207], v[98:101]
	v_mfma_i32_16x16x64_i8 v[98:101], v[62:65], v[208:211], v[98:101]
	v_mfma_i32_16x16x64_i8 v[126:129], v[146:149], v[174:177], v[126:129]
	v_mfma_i32_16x16x64_i8 v[126:129], v[150:153], v[178:181], v[126:129]
	v_mfma_i32_16x16x64_i8 v[110:113], v[146:149], v[182:185], v[110:113]
	v_mfma_i32_16x16x64_i8 v[110:113], v[150:153], v[186:189], v[110:113]
	v_mfma_i32_16x16x64_i8 v[94:97], v[146:149], v[190:193], v[94:97]
	v_mfma_i32_16x16x64_i8 v[94:97], v[150:153], v[200:203], v[94:97]
	v_mfma_i32_16x16x64_i8 v[86:89], v[146:149], v[204:207], v[86:89]
	v_mfma_i32_16x16x64_i8 v[86:89], v[150:153], v[208:211], v[86:89]
	v_mfma_i32_16x16x64_i8 v[118:121], v[154:157], v[174:177], v[118:121]
	v_mfma_i32_16x16x64_i8 v[118:121], v[158:161], v[178:181], v[118:121]
	v_mfma_i32_16x16x64_i8 v[102:105], v[154:157], v[182:185], v[102:105]
	v_mfma_i32_16x16x64_i8 v[102:105], v[158:161], v[186:189], v[102:105]
	v_mfma_i32_16x16x64_i8 v[90:93], v[154:157], v[190:193], v[90:93]
	v_mfma_i32_16x16x64_i8 v[90:93], v[158:161], v[200:203], v[90:93]
	v_mfma_i32_16x16x64_i8 v[82:85], v[154:157], v[204:207], v[82:85]
	v_mfma_i32_16x16x64_i8 v[82:85], v[158:161], v[208:211], v[82:85]
	s_barrier
	s_add_u32 s100, s30, 0xfff80080
	s_addc_u32 s101, s31, -1
	s_add_i32 s30, s42, s81
	s_add_u32 s98, s28, 0x80
	s_addc_u32 s99, s29, 0
	s_mov_b32 m0, s30
	ds_read_b128 v[174:177], v250 offset:49152
	ds_read_b128 v[178:181], v250 offset:50176
	ds_read_b128 v[182:185], v250 offset:51200
	ds_read_b128 v[186:189], v250 offset:52224
	ds_read_b128 v[190:193], v250 offset:53248
	ds_read_b128 v[200:203], v250 offset:54272
	ds_read_b128 v[204:207], v250 offset:55296
	ds_read_b128 v[208:211], v250 offset:56320
	global_load_lds_dwordx4 v164, s[98:99]
	s_add_i32 m0, s30, 0x2000
	s_add_u32 s28, s28, 0x80080
	s_addc_u32 s29, s29, 0
	s_add_i32 s30, s43, s81
	global_load_lds_dwordx4 v168, s[98:99]
	s_mov_b32 m0, s30
	s_nop 0
	global_load_lds_dwordx4 v164, s[28:29]
	s_add_i32 m0, s30, 0x2000
	s_nop 0
	global_load_lds_dwordx4 v168, s[28:29]
	s_mov_b32 m0, s15
	s_nop 0
	global_load_lds_dwordx4 v162, s[100:101]
	s_waitcnt vmcnt(7)
	s_waitcnt lgkmcnt(0)
	s_barrier
	s_waitcnt lgkmcnt(0)
	v_mfma_i32_16x16x64_i8 v[78:81], v[34:37], v[174:177], v[78:81]
	v_mfma_i32_16x16x64_i8 v[78:81], v[38:41], v[178:181], v[78:81]
	v_mfma_i32_16x16x64_i8 v[70:73], v[34:37], v[182:185], v[70:73]
	v_mfma_i32_16x16x64_i8 v[70:73], v[38:41], v[186:189], v[70:73]
	v_mfma_i32_16x16x64_i8 v[54:57], v[34:37], v[190:193], v[54:57]
	v_mfma_i32_16x16x64_i8 v[54:57], v[38:41], v[200:203], v[54:57]
	v_mfma_i32_16x16x64_i8 v[2:5], v[34:37], v[204:207], v[2:5]
	v_mfma_i32_16x16x64_i8 v[38:41], v[38:41], v[208:211], v[2:5]
	v_mfma_i32_16x16x64_i8 v[74:77], v[58:61], v[174:177], v[74:77]
	v_mfma_i32_16x16x64_i8 v[74:77], v[62:65], v[178:181], v[74:77]
	v_mfma_i32_16x16x64_i8 v[66:69], v[58:61], v[182:185], v[66:69]
	v_mfma_i32_16x16x64_i8 v[66:69], v[62:65], v[186:189], v[66:69]
	v_mfma_i32_16x16x64_i8 v[50:53], v[58:61], v[190:193], v[50:53]
	v_mfma_i32_16x16x64_i8 v[50:53], v[62:65], v[200:203], v[50:53]
	v_mfma_i32_16x16x64_i8 v[2:5], v[58:61], v[204:207], v[6:9]
	v_mfma_i32_16x16x64_i8 v[34:37], v[62:65], v[208:211], v[2:5]
	v_mfma_i32_16x16x64_i8 v[2:5], v[146:149], v[174:177], v[10:13]
	v_mfma_i32_16x16x64_i8 v[62:65], v[150:153], v[178:181], v[2:5]
	v_mfma_i32_16x16x64_i8 v[2:5], v[154:157], v[174:177], v[14:17]
	v_mfma_i32_16x16x64_i8 v[58:61], v[158:161], v[178:181], v[2:5]
	v_mfma_i32_16x16x64_i8 v[2:5], v[146:149], v[182:185], v[46:49]
	v_mfma_i32_16x16x64_i8 v[46:49], v[150:153], v[186:189], v[2:5]
	v_mfma_i32_16x16x64_i8 v[2:5], v[154:157], v[182:185], v[42:45]
	v_mfma_i32_16x16x64_i8 v[42:45], v[158:161], v[186:189], v[2:5]
	v_mfma_i32_16x16x64_i8 v[2:5], v[146:149], v[190:193], v[30:33]
	v_mfma_i32_16x16x64_i8 v[30:33], v[150:153], v[200:203], v[2:5]
	v_mfma_i32_16x16x64_i8 v[2:5], v[154:157], v[190:193], v[26:29]
	v_mfma_i32_16x16x64_i8 v[26:29], v[158:161], v[200:203], v[2:5]
	v_mfma_i32_16x16x64_i8 v[2:5], v[146:149], v[204:207], v[22:25]
	v_mfma_i32_16x16x64_i8 v[22:25], v[150:153], v[208:211], v[2:5]
	v_mfma_i32_16x16x64_i8 v[2:5], v[154:157], v[204:207], v[18:21]
	v_mfma_i32_16x16x64_i8 v[18:21], v[158:161], v[208:211], v[2:5]
	s_barrier
	s_add_i32 s41, s41, 2
	s_add_u32 s0, s0, 0x100
	s_addc_u32 s1, s1, 0
	s_add_u32 s35, s35, 0x100
	s_addc_u32 s40, s40, 0
	s_cmp_gt_u32 s41, 29
	s_cbranch_scc0 .LBB0_300
	s_and_b64 vcc, exec, s[52:53]
	s_cbranch_vccz .LBB0_303
	s_barrier
